# chain LDS-DMA duty moved to waves 2,3,6,7 so the two compute waves have their SIMDs to themselves; rest as previous
# baseline (speedup 1.0000x reference)
; #define LAS __attribute__((address_space(3)))
; #define CH_RAWBAR() do { asm volatile("s_waitcnt lgkmcnt(0)" ::: "memory"); __builtin_amdgcn_s_barrier(); asm volatile("" ::: "memory"); } while (0)
; #define CH_WAIT(EX) do { if (wave < 3) CH_WAITN(8 + (EX)); else if (wave == 3) CH_WAITN(6 + (EX)); else CH_WAITN(6); } while (0)
; __device__ __forceinline__ void ch_issue(const unsigned char* Rl, LAS unsigned char* dst, int wave) {
;     __builtin_amdgcn_global_load_lds((const unsigned*)(Rl + wave * 1024), (LAS unsigned*)(dst + wave * 1024), 16, 0, 0);
;     __builtin_amdgcn_global_load_lds((const unsigned*)(Rl + (wave + 8) * 1024), (LAS unsigned*)(dst + (wave + 8) * 1024), 16, 0, 0);
;     __builtin_amdgcn_global_load_lds((const unsigned*)(Rl + (wave + 16) * 1024), (LAS unsigned*)(dst + (wave + 16) * 1024), 16, 0, 0);
;     if (wave < 3) __builtin_amdgcn_global_load_lds((const unsigned*)(Rl + (wave + 24) * 1024), (LAS unsigned*)(dst + (wave + 24) * 1024), 16, 0, 0);
; }
; __device__ __forceinline__ void hgrn_chain(const unsigned char* REC, const float* s0, float* sout, bf16_t* MIX,
;                                            int cidx0, int nchunks, int h, int vhalf, LAS unsigned char* lds, int wave, int lane) {
;     ...
;     bf16_t* mo = MIX + (size_t)(cidx0 * 32 + c16) * D + 1024 + h * 128 + v0 + 4 * g;
;     const unsigned char* Rl = REC + ((size_t)cidx0 * 8 + h) * REC_STRIDE + lane * 16;
;     const unsigned char* Rlast = Rl + (size_t)(nchunks - 1) * 8 * REC_STRIDE;
;     asm volatile("s_waitcnt vmcnt(0)" ::: "memory");
;     const unsigned char* Ri = Rl;
; #pragma unroll
;     for (int cc = 0; cc < CH_NS - 1; ++cc) { ch_issue(Ri, lds + cc * CH_SLOT, wave); Ri = Ri < Rlast ? Ri + 8 * REC_STRIDE : Rlast; }
;     CH_WAIT(0);
;     CH_RAWBAR();
.LBB0_595:
	s_lshl_b32 s6, s79, 3
	s_and_b32 s8, s6, 0xffffff00
	s_ashr_i32 s10, s79, 2
	s_ashr_i32 s9, s8, 31
	s_and_b32 s11, s10, 7
	s_lshl_b64 s[6:7], s[8:9], 3
	s_or_b32 s6, s6, s11
	s_mulk_i32 s7, 0x6a00
	s_mul_hi_u32 s9, s6, 0x6a00
	s_add_i32 s9, s9, s7
	s_mulk_i32 s6, 0x6a00
	s_waitcnt vmcnt(0)
	v_mov_b32_e32 v10, v128
	s_add_u32 s6, s94, s6
	s_addc_u32 s7, s95, s9
	v_lshlrev_b32_e32 v120, 4, v10
	v_lshl_add_u64 v[0:1], s[6:7], 0, v[120:121]
	s_waitcnt vmcnt(0)
	v_readlane_b32 s12, v236, 35
	s_bitcmp1_b32 s12, 1
	s_cbranch_scc0 .Lch_pro_done
	s_and_b32 s13, s12, 1
	s_lshr_b32 s12, s12, 2
	s_lshl_b32 s12, s12, 1
	s_or_b32 s12, s12, s13
	s_mul_i32 s100, s12, 0x1c00
	s_add_u32 s98, s6, s100
	s_addc_u32 s99, s7, 0
	s_movk_i32 s101, 0x1800
	s_cmp_eq_u32 s96, 0x1c00
	s_cselect_b32 s101, 0x1400, s101
	v_mov_b32_e32 v164, v120
	v_add_u32_e32 v165, 0x400, v120
	v_add_u32_e32 v166, 0x800, v120
	v_add_u32_e32 v167, 0xc00, v120
	v_add_u32_e32 v168, 0x1000, v120
	v_add_u32_e32 v169, 0x1400, v120
	v_add_u32_e32 v170, s101, v120
	s_mov_b64 s[12:13], s[98:99]
	s_mov_b32 s6, s100
	s_mov_b32 m0, s6
	s_nop 0
	global_load_lds_dwordx4 v164, s[12:13]
	s_add_i32 m0, s6, 0x400
	s_nop 0
	global_load_lds_dwordx4 v165, s[12:13]
	s_add_i32 m0, s6, 0x800
	s_nop 0
	global_load_lds_dwordx4 v166, s[12:13]
	s_add_i32 m0, s6, 0xc00
	s_nop 0
	global_load_lds_dwordx4 v167, s[12:13]
	s_add_i32 m0, s6, 0x1000
	s_nop 0
	global_load_lds_dwordx4 v168, s[12:13]
	s_add_i32 m0, s6, 0x1400
	s_nop 0
	global_load_lds_dwordx4 v169, s[12:13]
	s_add_i32 m0, s6, s101
	s_nop 0
	global_load_lds_dwordx4 v170, s[12:13]
	s_add_u32 s12, s98, 0x35000
	s_addc_u32 s13, s99, 0
	s_add_i32 s6, s100, 0x6c00
	s_mov_b32 m0, s6
	s_nop 0
	global_load_lds_dwordx4 v164, s[12:13]
	s_add_i32 m0, s6, 0x400
	s_nop 0
	global_load_lds_dwordx4 v165, s[12:13]
	s_add_i32 m0, s6, 0x800
	s_nop 0
	global_load_lds_dwordx4 v166, s[12:13]
	s_add_i32 m0, s6, 0xc00
	s_nop 0
	global_load_lds_dwordx4 v167, s[12:13]
	s_add_i32 m0, s6, 0x1000
	s_nop 0
	global_load_lds_dwordx4 v168, s[12:13]
	s_add_i32 m0, s6, 0x1400
	s_nop 0
	global_load_lds_dwordx4 v169, s[12:13]
	s_add_i32 m0, s6, s101
	s_nop 0
	global_load_lds_dwordx4 v170, s[12:13]
	s_add_u32 s12, s98, 0x6a000
	s_addc_u32 s13, s99, 0
	s_add_i32 s6, s100, 0xd800
	s_mov_b32 m0, s6
	s_nop 0
	global_load_lds_dwordx4 v164, s[12:13]
	s_add_i32 m0, s6, 0x400
	s_nop 0
	global_load_lds_dwordx4 v165, s[12:13]
	s_add_i32 m0, s6, 0x800
	s_nop 0
	global_load_lds_dwordx4 v166, s[12:13]
	s_add_i32 m0, s6, 0xc00
	s_nop 0
	global_load_lds_dwordx4 v167, s[12:13]
	s_add_i32 m0, s6, 0x1000
	s_nop 0
	global_load_lds_dwordx4 v168, s[12:13]
	s_add_i32 m0, s6, 0x1400
	s_nop 0
	global_load_lds_dwordx4 v169, s[12:13]
	s_add_i32 m0, s6, s101
	s_nop 0
	global_load_lds_dwordx4 v170, s[12:13]
	s_waitcnt vmcnt(14)

; __device__ __forceinline__ void hgrn_chain(const unsigned char* REC, const float* s0, float* sout, bf16_t* MIX,
;                                            int cidx0, int nchunks, int h, int vhalf, LAS unsigned char* lds, int wave, int lane) {
;     ...
;     for (int c = 0; c < nchunks; ++c) {
;         ch_issue(Ri, lds + islot * CH_SLOT, wave); Ri = Ri < Rlast ? Ri + 8 * REC_STRIDE : Rlast;
;         islot = islot == CH_NS - 1 ? 0 : islot + 1;
;         const LAS unsigned char* R = lds + slot * CH_SLOT;
;         slot = slot == CH_NS - 1 ? 0 : slot + 1;
;         if (comp) {
;             bf16x8 QDf[2][4], KEf[8], ITf, Af[2]; f32x4 DEC[8];
; #pragma unroll
;             for (int kb = 0; kb < 8; ++kb) { DEC[kb] = *(const LAS f32x4*)(R + R_DEC + (16 * kb + 4 * g) * 4); KEf[kb] = *(const LAS bf16x8*)(R + R_KE + ((16 * kb + c16) * 32 + 8 * g) * 2); }
;             ITf = *(const LAS bf16x8*)(R + R_IT + ((v0 + c16) * 32 + 8 * g) * 2);
; #pragma unroll
;             for (int tb = 0; tb < 2; ++tb) {
;                 Af[tb] = *(const LAS bf16x8*)(R + R_A + ((16 * tb + c16) * 32 + 8 * g) * 2);
; #pragma unroll
;                 for (int kk = 0; kk < 4; ++kk) QDf[tb][kk] = *(const LAS bf16x8*)(R + R_QD + ((tb * 4 + kk) * 64 + lane) * 16);
;             }
;             bf16x8 Sb[4];
; #pragma unroll
;             for (int kk = 0; kk < 4; ++kk) {
;                 u32x4 sb; sb.x = cvt_pk_bf16(S[2 * kk][0], S[2 * kk][1]); sb.y = cvt_pk_bf16(S[2 * kk][2], S[2 * kk][3]);
;                 sb.z = cvt_pk_bf16(S[2 * kk + 1][0], S[2 * kk + 1][1]); sb.w = cvt_pk_bf16(S[2 * kk + 1][2], S[2 * kk + 1][3]);
;                 Sb[kk] = __builtin_bit_cast(bf16x8, sb);
;             }
; #pragma unroll
;             for (int kb = 0; kb < 8; ++kb) S[kb] = __builtin_amdgcn_mfma_f32_16x16x32_bf16(KEf[kb], ITf, S[kb] * DEC[kb], 0, 0, 0);
;             f32x4 o0 = {0.f, 0.f, 0.f, 0.f}, o1 = o0;
;             o0 = __builtin_amdgcn_mfma_f32_16x16x32_bf16(ITf, Af[0], o0, 0, 0, 0);
;             o1 = __builtin_amdgcn_mfma_f32_16x16x32_bf16(ITf, Af[1], o1, 0, 0, 0);
; #pragma unroll
;             for (int kk = 0; kk < 4; ++kk) { o0 = __builtin_amdgcn_mfma_f32_16x16x32_bf16(Sb[kk], QDf[0][kk], o0, 0, 0, 0); o1 = __builtin_amdgcn_mfma_f32_16x16x32_bf16(Sb[kk], QDf[1][kk], o1, 0, 0, 0); }
;             u32x2 w; w.x = cvt_pk_bf16(o0[0], o0[1]); w.y = cvt_pk_bf16(o0[2], o0[3]);
.LBB0_605:
	v_readlane_b32 s12, v236, 35
	s_cmp_lt_u32 s12, 2
	s_cbranch_scc1 .Lch_comp_new
	s_mov_b64 s[8:9], -1
	s_bitcmp1_b32 s12, 1
	s_cbranch_scc0 .LBB0_604
	s_add_i32 s12, s11, 3
	s_min_u32 s12, s12, 0xff
	s_mul_i32 s12, s12, 0x35000
	s_add_u32 s12, s98, s12
	s_addc_u32 s13, s99, 0
	s_mul_i32 s6, s15, 0x6c00
	s_add_i32 s6, s6, s100
	s_mov_b32 m0, s6
	s_nop 0
	global_load_lds_dwordx4 v164, s[12:13]
	s_add_i32 m0, s6, 0x400
	s_nop 0
	global_load_lds_dwordx4 v165, s[12:13]
	s_add_i32 m0, s6, 0x800
	s_nop 0
	global_load_lds_dwordx4 v166, s[12:13]
	s_add_i32 m0, s6, 0xc00
	s_nop 0
	global_load_lds_dwordx4 v167, s[12:13]
	s_add_i32 m0, s6, 0x1000
	s_nop 0
	global_load_lds_dwordx4 v168, s[12:13]
	s_add_i32 m0, s6, 0x1400
	s_nop 0
	global_load_lds_dwordx4 v169, s[12:13]
	s_add_i32 m0, s6, s101
	s_nop 0
	global_load_lds_dwordx4 v170, s[12:13]
	s_mov_b64 s[8:9], -1
	s_waitcnt vmcnt(14)
	s_branch .LBB0_604
.Lch_comp_new:
.Lch_comp_loop:
	s_mul_i32 s12, s16, 0x6c00
	v_add_u32_e32 v36, s12, v61
	v_add_u32_e32 v39, s12, v120
	v_add_u32_e32 v37, v36, v63
	v_add_u32_e32 v38, v36, v62
	ds_read_b128 v[32:35], v38 offset:16384
	ds_read_b128 v[164:167], v36 offset:26624
	ds_read_b128 v[196:199], v37 offset:8192
	ds_read_b128 v[168:171], v36 offset:26688
	ds_read_b128 v[200:203], v37 offset:9216
	ds_read_b128 v[172:175], v36 offset:26752
	ds_read_b128 v[204:207], v37 offset:10240
	ds_read_b128 v[176:179], v36 offset:26816
	ds_read_b128 v[208:211], v37 offset:11264
	ds_read_b128 v[180:183], v36 offset:26880
	ds_read_b128 v[212:215], v37 offset:12288
	ds_read_b128 v[184:187], v36 offset:26944
	ds_read_b128 v[216:219], v37 offset:13312
	ds_read_b128 v[188:191], v36 offset:27008
	ds_read_b128 v[220:223], v37 offset:14336
	s_mov_b64 s[8:9], 0
	v_cvt_pk_bf16_f32 v110, v28, v29
	v_cvt_pk_bf16_f32 v111, v30, v31
	v_cvt_pk_bf16_f32 v112, v24, v25
	v_cvt_pk_bf16_f32 v113, v26, v27
	v_cvt_pk_bf16_f32 v114, v20, v21
	v_cvt_pk_bf16_f32 v115, v22, v23
	v_cvt_pk_bf16_f32 v116, v16, v17
	v_cvt_pk_bf16_f32 v117, v18, v19
	v_cvt_pk_bf16_f32 v130, v12, v13
	v_cvt_pk_bf16_f32 v131, v14, v15
	v_cvt_pk_bf16_f32 v132, v8, v9
	v_cvt_pk_bf16_f32 v133, v10, v11
	v_cvt_pk_bf16_f32 v134, v4, v5
	v_cvt_pk_bf16_f32 v135, v6, v7
	v_cvt_pk_bf16_f32 v136, v0, v1
	v_cvt_pk_bf16_f32 v137, v2, v3
	s_waitcnt lgkmcnt(12)
	v_pk_mul_f32 v[28:29], v[28:29], v[164:165]
	v_pk_mul_f32 v[30:31], v[30:31], v[166:167]
	ds_read_b128 v[192:195], v36 offset:27072
	ds_read_b128 v[224:227], v37 offset:15360
	v_mfma_f32_16x16x32_bf16 v[28:31], v[196:199], v[32:35], v[28:31]
	s_waitcnt lgkmcnt(12)
	v_pk_mul_f32 v[24:25], v[24:25], v[168:169]
	v_pk_mul_f32 v[26:27], v[26:27], v[170:171]
	ds_read_b128 v[228:231], v37 offset:24576
	ds_read_b128 v[232:235], v37 offset:25600
	v_mfma_f32_16x16x32_bf16 v[24:27], v[200:203], v[32:35], v[24:27]
	s_waitcnt lgkmcnt(12)
	v_pk_mul_f32 v[20:21], v[20:21], v[172:173]
	v_pk_mul_f32 v[22:23], v[22:23], v[174:175]
	ds_read_b128 v[78:81], v39
	ds_read_b128 v[82:85], v39 offset:4096
	v_mfma_f32_16x16x32_bf16 v[20:23], v[204:207], v[32:35], v[20:23]
	s_waitcnt lgkmcnt(12)
	v_pk_mul_f32 v[16:17], v[16:17], v[176:177]
	v_pk_mul_f32 v[18:19], v[18:19], v[178:179]
	ds_read_b128 v[86:89], v39 offset:1024
	ds_read_b128 v[90:93], v39 offset:5120
	v_mfma_f32_16x16x32_bf16 v[16:19], v[208:211], v[32:35], v[16:19]
	s_waitcnt lgkmcnt(12)
	v_pk_mul_f32 v[12:13], v[12:13], v[180:181]
	v_pk_mul_f32 v[14:15], v[14:15], v[182:183]
	ds_read_b128 v[94:97], v39 offset:2048
	ds_read_b128 v[98:101], v39 offset:6144
	v_mfma_f32_16x16x32_bf16 v[12:15], v[212:215], v[32:35], v[12:15]
	s_waitcnt lgkmcnt(12)
	v_pk_mul_f32 v[8:9], v[8:9], v[184:185]
	v_pk_mul_f32 v[10:11], v[10:11], v[186:187]
	ds_read_b128 v[102:105], v39 offset:3072
	ds_read_b128 v[106:109], v39 offset:7168
	v_mfma_f32_16x16x32_bf16 v[8:11], v[216:219], v[32:35], v[8:11]
	s_waitcnt lgkmcnt(12)
	v_pk_mul_f32 v[4:5], v[4:5], v[188:189]
	v_pk_mul_f32 v[6:7], v[6:7], v[190:191]
	s_nop 1
	v_mfma_f32_16x16x32_bf16 v[4:7], v[220:223], v[32:35], v[4:7]
	s_waitcnt lgkmcnt(10)
	v_pk_mul_f32 v[0:1], v[0:1], v[192:193]
	v_pk_mul_f32 v[2:3], v[2:3], v[194:195]
	s_nop 1
	v_mfma_f32_16x16x32_bf16 v[0:3], v[224:227], v[32:35], v[0:3]
	s_waitcnt lgkmcnt(8)
	v_mfma_f32_16x16x32_bf16 v[138:141], v[32:35], v[228:231], 0
	v_mfma_f32_16x16x32_bf16 v[146:149], v[32:35], v[232:235], 0
	s_waitcnt lgkmcnt(7)
	v_mfma_f32_16x16x32_bf16 v[138:141], v[110:113], v[78:81], v[138:141]
	s_waitcnt lgkmcnt(6)
	v_mfma_f32_16x16x32_bf16 v[146:149], v[110:113], v[82:85], v[146:149]
	s_waitcnt lgkmcnt(5)
	v_mfma_f32_16x16x32_bf16 v[138:141], v[114:117], v[86:89], v[138:141]
	s_waitcnt lgkmcnt(4)
	v_mfma_f32_16x16x32_bf16 v[146:149], v[114:117], v[90:93], v[146:149]
	s_waitcnt lgkmcnt(3)
	v_mfma_f32_16x16x32_bf16 v[138:141], v[130:133], v[94:97], v[138:141]
	s_waitcnt lgkmcnt(2)
	v_mfma_f32_16x16x32_bf16 v[146:149], v[130:133], v[98:101], v[146:149]
	s_waitcnt lgkmcnt(1)
	v_mfma_f32_16x16x32_bf16 v[138:141], v[134:137], v[102:105], v[138:141]
	s_waitcnt lgkmcnt(0)
	v_mfma_f32_16x16x32_bf16 v[146:149], v[134:137], v[106:109], v[146:149]
	s_mov_b32 s12, 0xffff0000
	s_nop 6
	v_cvt_pk_bf16_f32 v36, v138, v139
	v_cvt_pk_bf16_f32 v37, v140, v141
	v_add_co_u32_e32 v38, vcc, s12, v48
	v_cvt_pk_bf16_f32 v40, v146, v147
	s_nop 0
	v_addc_co_u32_e32 v39, vcc, -1, v49, vcc
	v_cvt_pk_bf16_f32 v41, v148, v149
	global_store_dwordx2 v[38:39], v[36:37], off
	global_store_dwordx2 v[48:49], v[40:41], off
	s_add_i32 s12, s16, 1
	s_cmp_lg_u32 s16, 3
	s_cselect_b32 s16, s12, 0
	s_add_i32 s11, s11, 1
	s_mov_b64 s[12:13], 0x20000
	v_lshl_add_u64 v[48:49], v[48:49], 0, s[12:13]
	s_waitcnt lgkmcnt(0)
	s_barrier
	s_cmpk_eq_i32 s11, 0x100
	s_cbranch_scc0 .Lch_comp_loop
	s_branch .LBB0_639
